# GEMM0: first K tile of the next output tile is loaded before the current tile's epilogue (prologue no longer issues those loads)
# speedup vs baseline: 1.0070x; 1.0070x over previous
.LBB0_368:
	s_cmpk_gt_i32 s42, 0xbf
	s_cbranch_scc1 .LBB0_521
	s_mov_b32 s43, s42
	s_mov_b32 s0, s42
	s_mul_hi_i32 s1, s0, 0x55555556
	s_lshr_b32 s4, s1, 31
	s_add_i32 s1, s1, s4
	s_mul_i32 s4, s1, 3
	s_sub_i32 s4, s0, s4
	s_lshl_b32 s4, s4, 3
	s_add_i32 s4, s4, s41
	s_lshl_b32 s4, s4, 7
	s_lshl_b32 s1, s1, 7
	v_lshrrev_b32_e32 v200, 3, v0
	v_and_b32_e32 v201, 7, v0
	v_lshlrev_b32_e32 v201, 4, v201
	v_add_u32_e32 v202, s1, v200
	v_add_u32_e32 v203, s4, v200
	s_movk_i32 s0, 0x880
	v_mul_lo_u32 v202, v202, s0
	v_mul_lo_u32 v203, v203, s0
	v_add_u32_e32 v202, v202, v201
	v_add_u32_e32 v203, v203, v201
	v_add_u32_e32 v210, 0x11000, v202
	v_add_u32_e32 v211, 0x22000, v202
	v_add_u32_e32 v212, 0x33000, v202
	v_add_u32_e32 v213, 0x11000, v203
	v_add_u32_e32 v214, 0x22000, v203
	v_add_u32_e32 v215, 0x33000, v203
	global_load_dwordx4 v[164:167], v202, s[66:67]
	global_load_dwordx4 v[168:171], v210, s[66:67]
	global_load_dwordx4 v[172:175], v211, s[66:67]
	global_load_dwordx4 v[176:179], v212, s[66:67]
	global_load_dwordx4 v[180:183], v203, s[2:3]
	global_load_dwordx4 v[184:187], v213, s[2:3]
	global_load_dwordx4 v[192:195], v214, s[2:3]
	global_load_dwordx4 v[196:199], v215, s[2:3]
	s_branch .LBB0_372

.LBB0_372:
	s_mul_hi_i32 s0, s43, 0x55555556
	s_lshr_b32 s1, s0, 31
	s_add_i32 s0, s0, s1
	s_lshl_b32 s12, s0, 7
	s_mul_i32 s0, s0, 3
	s_sub_i32 s0, s43, s0
	v_mov_b32_e32 v1, v0
	s_lshl_b32 s44, s0, 3
	s_add_i32 s44, s44, s41
	s_waitcnt vmcnt(4)
	v_ashrrev_i32_e32 v8, 3, v1
	v_and_b32_e32 v9, 7, v1
	v_add_u32_e32 v4, s12, v8
	v_mov_b64_e32 v[2:3], s[66:67]
	s_lshl_b32 s13, s44, 7
	v_mad_i64_i32 v[2:3], s[0:1], v4, s58, v[2:3]
	v_lshlrev_b32_e32 v106, 4, v9
	v_lshl_add_u64 v[98:99], v[2:3], 0, v[106:107]
	v_add_u32_e32 v4, s13, v8
	v_mov_b64_e32 v[2:3], s[2:3]
	v_mad_i64_i32 v[2:3], s[0:1], v4, s58, v[2:3]
	s_mov_b32 s0, 0x11000
	s_nop 0
	v_add_co_u32_e32 v4, vcc, s0, v98
	s_mov_b32 s1, 0x22000
	s_nop 0
	v_addc_co_u32_e32 v5, vcc, 0, v99, vcc
	v_add_co_u32_e32 v6, vcc, s1, v98
	s_mov_b32 s4, 0x33000
	s_nop 0
	v_addc_co_u32_e32 v7, vcc, 0, v99, vcc
	v_add_co_u32_e32 v4, vcc, s4, v98
	v_lshl_add_u64 v[100:101], v[2:3], 0, v[106:107]
	s_nop 0
	v_addc_co_u32_e32 v5, vcc, 0, v99, vcc
	v_add_co_u32_e32 v2, vcc, s0, v100
	s_nop 0
	v_addc_co_u32_e32 v3, vcc, 0, v101, vcc
	v_add_co_u32_e32 v4, vcc, s1, v100
	s_nop 0
	v_addc_co_u32_e32 v5, vcc, 0, v101, vcc
	v_add_co_u32_e32 v2, vcc, s4, v100
	v_lshrrev_b32_e32 v4, 5, v1
	s_nop 0
	v_addc_co_u32_e32 v3, vcc, 0, v101, vcc
	v_ashrrev_i32_e32 v3, 4, v1
	s_waitcnt vmcnt(11)
	v_xor_b32_e32 v10, v3, v1
	v_and_b32_e32 v3, 1, v3
	v_and_b32_e32 v4, 6, v4
	v_lshrrev_b32_e32 v2, 4, v1
	v_bfe_u32 v102, v1, 4, 2
	v_bfe_u32 v5, v1, 1, 3
	v_bitop3_b32 v3, v3, v9, v4 bitop3:0x36
	v_ashrrev_i32_e32 v103, 7, v1
	v_lshlrev_b32_e32 v105, 7, v8
	v_bitop3_b32 v2, v2, v5, 3 bitop3:0x6c
	v_bitop3_b32 v5, v102, v5, 4 bitop3:0x36
	v_lshlrev_b32_e32 v4, 4, v10
	s_movk_i32 s0, 0x70
	v_lshlrev_b32_e32 v111, 4, v3
	v_and_b32_e32 v104, 15, v1
	v_lshlrev_b32_e32 v6, 1, v1
	v_and_b32_e32 v7, 0x43, v1
	v_lshlrev_b32_e32 v8, 13, v103
	v_lshlrev_b32_e32 v106, 4, v2
	v_lshlrev_b32_e32 v109, 4, v5
	v_and_or_b32 v110, v4, s0, v105
	v_or_b32_e32 v2, v105, v111
	v_lshlrev_b32_e32 v11, 7, v104
	v_and_or_b32 v6, v6, 24, v7
	v_or_b32_e32 v3, v106, v8
	v_or_b32_e32 v4, v109, v8
	v_lshlrev_b32_e32 v108, 7, v6
	s_mov_b64 s[0:1], 0
	v_lshl_add_u64 v[224:225], v[98:99], 0, s[0:1]
	global_load_dwordx4 v[224:227], v[224:225], off offset:128
	s_add_u32 s6, s0, 0x11000
	s_addc_u32 s7, s1, 0
	v_lshl_add_u64 v[228:229], v[98:99], 0, s[6:7]
	global_load_dwordx4 v[228:231], v[228:229], off offset:128
	s_add_u32 vcc_lo, s0, 0x22000
	s_addc_u32 vcc_hi, s1, 0
	v_lshl_add_u64 v[232:233], v[98:99], 0, vcc
	global_load_dwordx4 v[232:235], v[232:233], off offset:128
	s_add_u32 s6, s0, 0x33000
	s_addc_u32 s7, s1, 0
	v_lshl_add_u64 v[236:237], v[98:99], 0, s[6:7]
	global_load_dwordx4 v[236:239], v[236:237], off offset:128
	v_lshl_add_u64 v[240:241], v[100:101], 0, s[0:1]
	global_load_dwordx4 v[240:243], v[240:241], off offset:128
	s_add_u32 vcc_lo, s0, 0x11000
	s_addc_u32 vcc_hi, s1, 0
	v_lshl_add_u64 v[244:245], v[100:101], 0, vcc
	global_load_dwordx4 v[244:247], v[244:245], off offset:128
	s_add_u32 s6, s0, 0x22000
	s_addc_u32 s7, s1, 0
	v_lshl_add_u64 v[248:249], v[100:101], 0, s[6:7]
	global_load_dwordx4 v[248:251], v[248:249], off offset:128
	s_add_u32 vcc_lo, s0, 0x33000
	s_addc_u32 vcc_hi, s1, 0
	v_lshl_add_u64 v[252:253], v[100:101], 0, vcc
	global_load_dwordx4 v[252:255], v[252:253], off offset:128
	v_add_u32_e32 v112, v3, v11
	v_add_u32_e32 v113, v4, v11
	s_waitcnt vmcnt(15)
	ds_write_b128 v110, v[164:167]
	s_waitcnt vmcnt(14)
	ds_write_b128 v110, v[168:171] offset:4096
	s_waitcnt vmcnt(13)
	ds_write_b128 v110, v[172:175] offset:8192
	s_waitcnt vmcnt(12)
	ds_write_b128 v110, v[176:179] offset:12288
	s_waitcnt vmcnt(11)
	ds_write_b128 v2, v[180:183] offset:16384
	s_waitcnt vmcnt(10)
	ds_write_b128 v2, v[184:187] offset:20480
	s_waitcnt vmcnt(9)
	ds_write_b128 v2, v[192:195] offset:24576
	s_waitcnt vmcnt(8)
	ds_write_b128 v2, v[196:199] offset:28672
	v_mov_b32_e32 v2, 0
	v_mov_b32_e32 v3, v2
	v_mov_b32_e32 v4, v2
	v_mov_b32_e32 v5, v2
	v_mov_b32_e32 v6, v2
	v_mov_b32_e32 v7, v2
	v_mov_b32_e32 v8, v2
	v_mov_b32_e32 v9, v2
	v_mov_b32_e32 v10, v2
	v_mov_b32_e32 v11, v2
	v_mov_b32_e32 v12, v2
	v_mov_b32_e32 v13, v2
	v_mov_b32_e32 v14, v2
	v_mov_b32_e32 v15, v2
	v_mov_b32_e32 v16, v2
	v_mov_b32_e32 v17, v2
	v_mov_b32_e32 v18, v2
	v_mov_b32_e32 v19, v2
	v_mov_b32_e32 v20, v2
	v_mov_b32_e32 v21, v2
	v_mov_b32_e32 v22, v2
	v_mov_b32_e32 v23, v2
	v_mov_b32_e32 v24, v2
	v_mov_b32_e32 v25, v2
	v_mov_b32_e32 v26, v2
	v_mov_b32_e32 v27, v2
	v_mov_b32_e32 v28, v2
	v_mov_b32_e32 v29, v2
	v_mov_b32_e32 v30, v2
	v_mov_b32_e32 v31, v2
	v_mov_b32_e32 v32, v2
	v_mov_b32_e32 v33, v2
	v_mov_b32_e32 v34, v2
	v_mov_b32_e32 v35, v2
	v_mov_b32_e32 v36, v2
	v_mov_b32_e32 v37, v2
	v_mov_b32_e32 v38, v2
	v_mov_b32_e32 v39, v2
	v_mov_b32_e32 v40, v2
	v_mov_b32_e32 v41, v2
	v_mov_b32_e32 v42, v2
	v_mov_b32_e32 v43, v2
	v_mov_b32_e32 v44, v2
	v_mov_b32_e32 v45, v2
	v_mov_b32_e32 v46, v2
	v_mov_b32_e32 v47, v2
	v_mov_b32_e32 v48, v2
	v_mov_b32_e32 v49, v2
	v_mov_b32_e32 v50, v2
	v_mov_b32_e32 v51, v2
	v_mov_b32_e32 v52, v2
	v_mov_b32_e32 v53, v2
	v_mov_b32_e32 v54, v2
	v_mov_b32_e32 v55, v2
	v_mov_b32_e32 v56, v2
	v_mov_b32_e32 v57, v2
	v_mov_b32_e32 v58, v2
	v_mov_b32_e32 v59, v2
	v_mov_b32_e32 v60, v2
	v_mov_b32_e32 v61, v2
	v_mov_b32_e32 v66, v2
	v_mov_b32_e32 v67, v2
	v_mov_b32_e32 v68, v2
	v_mov_b32_e32 v69, v2
	v_add_u32_e32 v188, v106, v108
	v_add_u32_e32 v189, v109, v108
	v_add_u32_e32 v190, v105, v111
	s_waitcnt lgkmcnt(0)
	s_barrier
	s_branch .LBB0_374

.LBB0_378:
	s_cmpk_gt_i32 s43, 0x7f
	s_cbranch_scc1 .Lpf_skip
	s_add_i32 s0, s43, 64
	s_mul_hi_i32 s1, s0, 0x55555556
	s_lshr_b32 s4, s1, 31
	s_add_i32 s1, s1, s4
	s_mul_i32 s4, s1, 3
	s_sub_i32 s4, s0, s4
	s_lshl_b32 s4, s4, 3
	s_add_i32 s4, s4, s41
	s_lshl_b32 s4, s4, 7
	s_lshl_b32 s1, s1, 7
	v_lshrrev_b32_e32 v200, 3, v0
	v_and_b32_e32 v201, 7, v0
	v_lshlrev_b32_e32 v201, 4, v201
	v_add_u32_e32 v202, s1, v200
	v_add_u32_e32 v203, s4, v200
	s_movk_i32 s0, 0x880
	v_mul_lo_u32 v202, v202, s0
	v_mul_lo_u32 v203, v203, s0
	v_add_u32_e32 v202, v202, v201
	v_add_u32_e32 v203, v203, v201
	v_add_u32_e32 v210, 0x11000, v202
	v_add_u32_e32 v211, 0x22000, v202
	v_add_u32_e32 v212, 0x33000, v202
	v_add_u32_e32 v213, 0x11000, v203
	v_add_u32_e32 v214, 0x22000, v203
	v_add_u32_e32 v215, 0x33000, v203
	global_load_dwordx4 v[164:167], v202, s[66:67]
	global_load_dwordx4 v[168:171], v210, s[66:67]
	global_load_dwordx4 v[172:175], v211, s[66:67]
	global_load_dwordx4 v[176:179], v212, s[66:67]
	global_load_dwordx4 v[180:183], v203, s[2:3]
	global_load_dwordx4 v[184:187], v213, s[2:3]
	global_load_dwordx4 v[192:195], v214, s[2:3]
	global_load_dwordx4 v[196:199], v215, s[2:3]
.Lpf_skip:
	v_and_b32_e32 v62, 64, v1
	v_or_b32_e32 v1, s12, v104
	v_lshl_add_u32 v1, v103, 6, v1
	v_lshlrev_b32_e32 v63, 3, v102
	v_or3_b32 v62, v63, v62, s13
	v_lshrrev_b32_e32 v63, 7, v1
	s_cmpk_lt_i32 s43, 0x60
	v_and_b32_e32 v63, 0xfffffe, v63
	v_readlane_b32 s4, v206, 46
	s_cselect_b64 s[54:55], -1, 0
	s_sub_i32 s0, s44, 21
	v_or_b32_e32 v63, s4, v63
	s_cmp_gt_u32 s0, 1
	v_lshlrev_b32_e32 v76, 8, v63
	s_movk_i32 s4, 0xcf
	s_cselect_b64 s[52:53], -1, 0
	s_sub_i32 s0, s44, 23
	v_and_or_b32 v70, v1, s4, v76
	v_mov_b64_e32 v[72:73], s[68:69]
	s_cmp_lt_u32 s0, 2
	v_ashrrev_i32_e32 v71, 31, v70
	v_mad_i64_i32 v[72:73], s[6:7], v1, s37, v[72:73]
	v_ashrrev_i32_e32 v63, 31, v62
	s_cselect_b64 s[0:1], -1, 0
	v_lshlrev_b64 v[64:65], 9, v[70:71]
	v_lshlrev_b64 v[70:71], 10, v[70:71]
	v_cvt_pk_bf16_f32 v78, v66, v67
	v_cvt_pk_bf16_f32 v79, v68, v69
	v_cvt_pk_bf16_f32 v80, v58, v59
	v_cvt_pk_bf16_f32 v81, v60, v61
	v_lshl_add_u64 v[72:73], v[62:63], 1, v[72:73]
	s_and_b64 vcc, exec, s[54:55]
	global_store_dwordx4 v[72:73], v[78:81], off
	s_cbranch_vccz .LBB0_390
	s_mov_b64 s[58:59], -1
	s_mov_b64 s[6:7], 0
	s_cmp_lt_i32 s44, 12
	s_mov_b64 s[56:57], 0
	s_cbranch_scc1 .LBB0_383
	s_cmp_eq_u32 s44, 12
	s_mov_b64 s[56:57], -1
	s_cbranch_scc0 .LBB0_382
	v_readlane_b32 s12, v208, 17
	v_readlane_b32 s18, v208, 23
	v_readlane_b32 s19, v208, 24
	s_mov_b64 s[4:5], 0x23fe800
	v_readlane_b32 s13, v208, 18
	v_lshl_add_u64 v[74:75], s[18:19], 0, v[64:65]
	v_lshl_add_u64 v[74:75], v[62:63], 2, v[74:75]
	v_readlane_b32 s14, v208, 19
	v_readlane_b32 s15, v208, 20
	v_readlane_b32 s16, v208, 21
	v_readlane_b32 s17, v208, 22
	v_readlane_b32 s20, v208, 25
	v_readlane_b32 s21, v208, 26
	v_readlane_b32 s22, v208, 27
	v_readlane_b32 s23, v208, 28
	v_readlane_b32 s24, v208, 29
	v_readlane_b32 s25, v208, 30
	v_readlane_b32 s26, v208, 31
	v_readlane_b32 s27, v208, 32
	v_lshl_add_u64 v[74:75], v[74:75], 0, s[4:5]
	s_mov_b64 s[56:57], 0
